# speedup vs baseline: 1.0013x; 1.0004x over previous
; template <class T> __device__ __forceinline__ void run_epilogue(const TileDesc& d, f32x4 (&acc)[8][4], const unsigned (&xcr)[32], int wr, int wc, int fr, int fq) {
;   switch (d.kind) {
;     case EPI_BF16:   EpiBf16{(bf16*)d.C, d.ldc}(acc, wr, wc, fr, fq); break;
;     case EPI_RELU2:  EpiRelu2{(bf16*)d.C, d.ldc}(acc, wr, wc, fr, fq); break;
;     case EPI_SCALE:  EpiScale{(bf16*)d.C, d.ldc, (const float*)d.e1}(acc, wr, wc, fr, fq); break;
;     case EPI_F32:    EpiF32{(float*)d.C, d.ldc}(acc, wr, wc, fr, fq); break;
;     case EPI_KV:     EpiKV{(bf16*)d.C, (bf16*)d.e0, d.ival}(acc, wr, wc, fr, fq); break;
;     case EPI_SOFTMAX: EpiSoftmax{(bf16*)d.C}(acc, wr, wc, fr, fq); break;
;     case EPI_SIGM:   EpiSigm{(unsigned char*)d.C, d.ldc}(acc, wr, wc, fr, fq); break;
.LBB0_394:
	s_mov_b64 s[16:17], -1
	s_mov_b64 s[4:5], 0
	s_cmp_lt_i32 s90, 3
	s_mov_b64 s[34:35], 0
	s_cbranch_scc1 .LBB0_445
	s_cmp_gt_i32 s90, 4
	s_cbranch_scc0 .LBB0_435
	s_cmp_gt_i32 s90, 5
	s_cbranch_scc0 .LBB0_400
	s_cmp_eq_u32 s90, 6
	s_mov_b64 s[34:35], -1
	s_cbranch_scc0 .LBB0_399
	v_mov_b32_e32 v147, v195
	v_mov_b32_e32 v148, v193
	v_mov_b32_e32 v149, v194
	v_mov_b32_e32 v144, v165
	v_mul_f32_e32 v152, 0xbfb8aa3b, v123
	v_lshlrev_b32_e32 v145, 6, v147
	v_lshlrev_b32_e32 v150, 2, v147
	v_lshlrev_b32_e32 v147, 15, v149
	v_lshlrev_b32_e32 v146, 4, v148
	v_lshl_add_u32 v147, v148, 2, v147
	v_lshlrev_b32_e32 v148, 8, v144
	v_add3_u32 v151, v147, v148, s89
	v_mul_f32_e32 v147, 0xbfb8aa3b, v124
	v_mul_f32_e32 v148, 0xbfb8aa3b, v125
	v_exp_f32_e32 v147, v147
	v_exp_f32_e32 v148, v148
	v_lshl_add_u32 v145, v149, 8, v145
	v_mul_f32_e32 v149, 0xbfb8aa3b, v127
	v_add_f32_e32 v147, 1.0, v147
	v_add_f32_e32 v148, 1.0, v148
	v_rcp_f32_e32 v147, v147
	v_rcp_f32_e32 v148, v148
	v_exp_f32_e32 v149, v149
	v_exp_f32_e32 v152, v152
	v_mul_f32_e32 v147, 0x437f0000, v147
	v_mul_f32_e32 v148, 0x437f0000, v148
	v_cvt_pk_u8_f32 v147, v147, 0, 0
	v_add_f32_e32 v149, 1.0, v149
	v_rcp_f32_e32 v149, v149
	v_cvt_pk_u8_f32 v147, v148, 1, v147
	v_mul_f32_e32 v148, 0xbfb8aa3b, v126
	v_exp_f32_e32 v148, v148
	v_mul_f32_e32 v149, 0x437f0000, v149
	v_add_f32_e32 v148, 1.0, v148
	v_rcp_f32_e32 v148, v148
	v_add_f32_e32 v152, 1.0, v152
	v_rcp_f32_e32 v152, v152
	v_mul_f32_e32 v148, 0x437f0000, v148
	v_mul_f32_e32 v152, 0x437f0000, v152
	v_mul_f32_e32 v153, 0xbfb8aa3b, v119
	v_cvt_pk_u8_f32 v148, v148, 2, v147
	v_cvt_pk_u8_f32 v148, v149, 3, v148
	v_xor_b32_e32 v147, v150, v144
	v_lshl_add_u32 v147, v147, 4, v151
	ds_write_b32 v147, v148
	v_mul_f32_e32 v148, 0xbfb8aa3b, v120
	v_mul_f32_e32 v149, 0xbfb8aa3b, v121
	v_exp_f32_e32 v148, v148
	v_exp_f32_e32 v149, v149
	v_exp_f32_e32 v153, v153
	v_add_f32_e32 v148, 1.0, v148
	v_add_f32_e32 v149, 1.0, v149
	v_rcp_f32_e32 v148, v148
	v_rcp_f32_e32 v149, v149
	v_add_f32_e32 v153, 1.0, v153
	v_rcp_f32_e32 v153, v153
	v_mul_f32_e32 v148, 0x437f0000, v148
	v_mul_f32_e32 v149, 0x437f0000, v149
	v_cvt_pk_u8_f32 v148, v148, 0, 0
	v_mul_f32_e32 v153, 0x437f0000, v153
	v_cvt_pk_u8_f32 v148, v149, 1, v148
	v_mul_f32_e32 v149, 0xbfb8aa3b, v122
	v_exp_f32_e32 v149, v149
	v_mul_f32_e32 v154, 0xbfb8aa3b, v115
	v_exp_f32_e32 v154, v154
	v_add_f32_e32 v149, 1.0, v149
	v_rcp_f32_e32 v149, v149
	v_add_f32_e32 v154, 1.0, v154
	v_rcp_f32_e32 v154, v154
	v_mul_f32_e32 v149, 0x437f0000, v149
	v_mul_f32_e32 v154, 0x437f0000, v154
	v_or3_b32 v145, v146, v145, v144
	v_cvt_pk_u8_f32 v149, v149, 2, v148
	v_cvt_pk_u8_f32 v149, v152, 3, v149
	v_bitop3_b32 v148, v150, v144, 1 bitop3:0x36
	v_lshl_add_u32 v148, v148, 4, v151
	ds_write_b32 v148, v149
	v_mul_f32_e32 v149, 0xbfb8aa3b, v116
	v_mul_f32_e32 v152, 0xbfb8aa3b, v117
	v_exp_f32_e32 v149, v149
	v_exp_f32_e32 v152, v152
	v_lshlrev_b32_e32 v146, 4, v144
	v_add_f32_e32 v149, 1.0, v149
	v_add_f32_e32 v152, 1.0, v152
	v_rcp_f32_e32 v149, v149
	v_rcp_f32_e32 v152, v152
	s_and_b32 s17, s13, 0xffff
	s_mov_b32 s16, s12
	v_mul_f32_e32 v149, 0x437f0000, v149
	v_mul_f32_e32 v152, 0x437f0000, v152
	v_cvt_pk_u8_f32 v149, v149, 0, 0
	s_mov_b32 s18, s10
	s_mov_b32 s19, s11
	v_cvt_pk_u8_f32 v149, v152, 1, v149
	v_mul_f32_e32 v152, 0xbfb8aa3b, v118
	v_exp_f32_e32 v152, v152
	s_nop 0
	v_add_f32_e32 v152, 1.0, v152
	v_rcp_f32_e32 v152, v152
	s_nop 0
	v_mul_f32_e32 v152, 0x437f0000, v152
	s_nop 0
	v_cvt_pk_u8_f32 v152, v152, 2, v149
	v_cvt_pk_u8_f32 v152, v153, 3, v152
	v_bitop3_b32 v149, v150, v144, 2 bitop3:0x36
	v_lshl_add_u32 v149, v149, 4, v151
	ds_write_b32 v149, v152
	v_mul_f32_e32 v152, 0xbfb8aa3b, v112
	v_mul_f32_e32 v153, 0xbfb8aa3b, v113
	v_exp_f32_e32 v152, v152
	v_exp_f32_e32 v153, v153
	v_bitop3_b32 v150, v150, v144, 3 bitop3:0x36
	v_lshl_add_u32 v150, v150, 4, v151
	v_add_f32_e32 v152, 1.0, v152
	v_add_f32_e32 v153, 1.0, v153
	v_rcp_f32_e32 v152, v152
	v_rcp_f32_e32 v153, v153
	v_mul_f32_e32 v151, 0xbfb8aa3b, v108
	v_exp_f32_e32 v151, v151
	v_mul_f32_e32 v152, 0x437f0000, v152
	v_mul_f32_e32 v153, 0x437f0000, v153
	v_cvt_pk_u8_f32 v152, v152, 0, 0
	v_add_f32_e32 v151, 1.0, v151
	v_rcp_f32_e32 v151, v151
	v_cvt_pk_u8_f32 v152, v153, 1, v152
	v_mul_f32_e32 v153, 0xbfb8aa3b, v114
	v_exp_f32_e32 v153, v153
	v_mul_f32_e32 v151, 0x437f0000, v151
	v_cvt_pk_u8_f32 v151, v151, 0, 0
	v_add_f32_e32 v153, 1.0, v153
	v_rcp_f32_e32 v153, v153
	s_nop 0
	v_mul_f32_e32 v153, 0x437f0000, v153
	s_nop 0
	v_cvt_pk_u8_f32 v152, v153, 2, v152
	v_cvt_pk_u8_f32 v152, v154, 3, v152
	ds_write_b32 v150, v152
	v_mul_f32_e32 v152, 0xbfb8aa3b, v109
	v_exp_f32_e32 v152, v152
	v_mul_f32_e32 v153, 0xbfb8aa3b, v111
	v_exp_f32_e32 v153, v153
	v_add_f32_e32 v152, 1.0, v152
	v_rcp_f32_e32 v152, v152
	v_add_f32_e32 v153, 1.0, v153
	v_rcp_f32_e32 v153, v153
	v_mul_f32_e32 v152, 0x437f0000, v152
	v_mul_f32_e32 v153, 0x437f0000, v153
	v_cvt_pk_u8_f32 v151, v152, 1, v151
	v_mul_f32_e32 v152, 0xbfb8aa3b, v110
	v_exp_f32_e32 v152, v152
	s_nop 0
	v_add_f32_e32 v152, 1.0, v152
	v_rcp_f32_e32 v152, v152
	s_nop 0
	v_mul_f32_e32 v152, 0x437f0000, v152
	s_nop 0
	v_cvt_pk_u8_f32 v151, v152, 2, v151
	v_cvt_pk_u8_f32 v151, v153, 3, v151
	ds_write_b32 v147, v151 offset:4096
	v_mul_f32_e32 v151, 0xbfb8aa3b, v104
	v_mul_f32_e32 v152, 0xbfb8aa3b, v105
	v_exp_f32_e32 v151, v151
	v_exp_f32_e32 v152, v152
	v_mul_f32_e32 v153, 0xbfb8aa3b, v107
	v_exp_f32_e32 v153, v153
	v_add_f32_e32 v151, 1.0, v151
	v_add_f32_e32 v152, 1.0, v152
	v_rcp_f32_e32 v151, v151
	v_rcp_f32_e32 v152, v152
	v_add_f32_e32 v153, 1.0, v153
	v_rcp_f32_e32 v153, v153
	v_mul_f32_e32 v151, 0x437f0000, v151
	v_mul_f32_e32 v152, 0x437f0000, v152
	v_cvt_pk_u8_f32 v151, v151, 0, 0
	v_mul_f32_e32 v153, 0x437f0000, v153
	v_cvt_pk_u8_f32 v151, v152, 1, v151
	v_mul_f32_e32 v152, 0xbfb8aa3b, v106
	v_exp_f32_e32 v152, v152
	s_nop 0
	v_add_f32_e32 v152, 1.0, v152
	v_rcp_f32_e32 v152, v152
	s_nop 0
	v_mul_f32_e32 v152, 0x437f0000, v152
	s_nop 0
	v_cvt_pk_u8_f32 v151, v152, 2, v151
	v_cvt_pk_u8_f32 v151, v153, 3, v151
	ds_write_b32 v148, v151 offset:4096
	v_mul_f32_e32 v151, 0xbfb8aa3b, v100
	v_mul_f32_e32 v152, 0xbfb8aa3b, v101
	v_exp_f32_e32 v151, v151
	v_exp_f32_e32 v152, v152
	v_mul_f32_e32 v153, 0xbfb8aa3b, v103
	v_exp_f32_e32 v153, v153
	v_add_f32_e32 v151, 1.0, v151
	v_add_f32_e32 v152, 1.0, v152
	v_rcp_f32_e32 v151, v151
	v_rcp_f32_e32 v152, v152
	v_add_f32_e32 v153, 1.0, v153
	v_rcp_f32_e32 v153, v153
	v_mul_f32_e32 v151, 0x437f0000, v151
	v_mul_f32_e32 v152, 0x437f0000, v152
	v_cvt_pk_u8_f32 v151, v151, 0, 0
	v_mul_f32_e32 v153, 0x437f0000, v153
	v_cvt_pk_u8_f32 v151, v152, 1, v151
	v_mul_f32_e32 v152, 0xbfb8aa3b, v102
	v_exp_f32_e32 v152, v152
	s_nop 0
	v_add_f32_e32 v152, 1.0, v152
	v_rcp_f32_e32 v152, v152
	s_nop 0
	v_mul_f32_e32 v152, 0x437f0000, v152
	s_nop 0
	v_cvt_pk_u8_f32 v151, v152, 2, v151
	v_cvt_pk_u8_f32 v151, v153, 3, v151
	ds_write_b32 v149, v151 offset:4096
	v_mul_f32_e32 v151, 0xbfb8aa3b, v96
	v_mul_f32_e32 v152, 0xbfb8aa3b, v97
	v_exp_f32_e32 v151, v151
	v_exp_f32_e32 v152, v152
	v_mul_f32_e32 v153, 0xbfb8aa3b, v99
	v_exp_f32_e32 v153, v153
	v_add_f32_e32 v151, 1.0, v151
	v_add_f32_e32 v152, 1.0, v152
	v_rcp_f32_e32 v151, v151
	v_rcp_f32_e32 v152, v152
	v_add_f32_e32 v153, 1.0, v153
	v_rcp_f32_e32 v153, v153
	v_mul_f32_e32 v151, 0x437f0000, v151
	v_mul_f32_e32 v152, 0x437f0000, v152
	v_cvt_pk_u8_f32 v151, v151, 0, 0
	v_mul_f32_e32 v153, 0x437f0000, v153
	v_cvt_pk_u8_f32 v151, v152, 1, v151
	v_mul_f32_e32 v152, 0xbfb8aa3b, v98
	v_exp_f32_e32 v152, v152
	s_nop 0
	v_add_f32_e32 v152, 1.0, v152
	v_rcp_f32_e32 v152, v152
	s_nop 0
	v_mul_f32_e32 v152, 0x437f0000, v152
	s_nop 0
	v_cvt_pk_u8_f32 v151, v152, 2, v151
	v_cvt_pk_u8_f32 v151, v153, 3, v151
	ds_write_b32 v150, v151 offset:4096
	v_mul_f32_e32 v151, 0xbfb8aa3b, v92
	v_mul_f32_e32 v152, 0xbfb8aa3b, v93
	v_exp_f32_e32 v151, v151
	v_exp_f32_e32 v152, v152
	v_mul_f32_e32 v153, 0xbfb8aa3b, v95
	v_exp_f32_e32 v153, v153
	v_add_f32_e32 v151, 1.0, v151
	v_add_f32_e32 v152, 1.0, v152
	v_rcp_f32_e32 v151, v151
	v_rcp_f32_e32 v152, v152
	v_add_f32_e32 v153, 1.0, v153
	v_rcp_f32_e32 v153, v153
	v_mul_f32_e32 v151, 0x437f0000, v151
	v_mul_f32_e32 v152, 0x437f0000, v152
	v_cvt_pk_u8_f32 v151, v151, 0, 0
	v_mul_f32_e32 v153, 0x437f0000, v153
	v_cvt_pk_u8_f32 v151, v152, 1, v151
	v_mul_f32_e32 v152, 0xbfb8aa3b, v94
	v_exp_f32_e32 v152, v152
	s_nop 0
	v_add_f32_e32 v152, 1.0, v152
	v_rcp_f32_e32 v152, v152
	s_nop 0
	v_mul_f32_e32 v152, 0x437f0000, v152
	s_nop 0
	v_cvt_pk_u8_f32 v151, v152, 2, v151
	v_cvt_pk_u8_f32 v151, v153, 3, v151
	ds_write_b32 v147, v151 offset:8192
	v_mul_f32_e32 v151, 0xbfb8aa3b, v88
	v_mul_f32_e32 v152, 0xbfb8aa3b, v89
	v_exp_f32_e32 v151, v151
	v_exp_f32_e32 v152, v152
	v_mul_f32_e32 v153, 0xbfb8aa3b, v91
	v_exp_f32_e32 v153, v153
	v_add_f32_e32 v151, 1.0, v151
	v_add_f32_e32 v152, 1.0, v152
	v_rcp_f32_e32 v151, v151
	v_rcp_f32_e32 v152, v152
	v_add_f32_e32 v153, 1.0, v153
	v_rcp_f32_e32 v153, v153
	v_mul_f32_e32 v151, 0x437f0000, v151
	v_mul_f32_e32 v152, 0x437f0000, v152
	v_cvt_pk_u8_f32 v151, v151, 0, 0
	v_mul_f32_e32 v153, 0x437f0000, v153
	v_cvt_pk_u8_f32 v151, v152, 1, v151
	v_mul_f32_e32 v152, 0xbfb8aa3b, v90
	v_exp_f32_e32 v152, v152
	s_nop 0
	v_add_f32_e32 v152, 1.0, v152
	v_rcp_f32_e32 v152, v152
	s_nop 0
	v_mul_f32_e32 v152, 0x437f0000, v152
	s_nop 0
	v_cvt_pk_u8_f32 v151, v152, 2, v151
	v_cvt_pk_u8_f32 v151, v153, 3, v151
	ds_write_b32 v148, v151 offset:8192
	v_mul_f32_e32 v151, 0xbfb8aa3b, v84
	v_mul_f32_e32 v152, 0xbfb8aa3b, v85
	v_exp_f32_e32 v151, v151
	v_exp_f32_e32 v152, v152
	v_mul_f32_e32 v153, 0xbfb8aa3b, v87
	v_exp_f32_e32 v153, v153
	v_add_f32_e32 v151, 1.0, v151
	v_add_f32_e32 v152, 1.0, v152
	v_rcp_f32_e32 v151, v151
	v_rcp_f32_e32 v152, v152
	v_add_f32_e32 v153, 1.0, v153
	v_rcp_f32_e32 v153, v153
	v_mul_f32_e32 v151, 0x437f0000, v151
	v_mul_f32_e32 v152, 0x437f0000, v152
	v_cvt_pk_u8_f32 v151, v151, 0, 0
	v_mul_f32_e32 v153, 0x437f0000, v153
	v_cvt_pk_u8_f32 v151, v152, 1, v151
	v_mul_f32_e32 v152, 0xbfb8aa3b, v86
	v_exp_f32_e32 v152, v152
	s_nop 0
	v_add_f32_e32 v152, 1.0, v152
	v_rcp_f32_e32 v152, v152
	s_nop 0
	v_mul_f32_e32 v152, 0x437f0000, v152
	s_nop 0
	v_cvt_pk_u8_f32 v151, v152, 2, v151
	v_cvt_pk_u8_f32 v151, v153, 3, v151
	ds_write_b32 v149, v151 offset:8192
	v_mul_f32_e32 v151, 0xbfb8aa3b, v80
	v_mul_f32_e32 v152, 0xbfb8aa3b, v81
	v_exp_f32_e32 v151, v151
	v_exp_f32_e32 v152, v152
	v_mul_f32_e32 v153, 0xbfb8aa3b, v83
	v_exp_f32_e32 v153, v153
	v_add_f32_e32 v151, 1.0, v151
	v_add_f32_e32 v152, 1.0, v152
	v_rcp_f32_e32 v151, v151
	v_rcp_f32_e32 v152, v152
	v_add_f32_e32 v153, 1.0, v153
	v_rcp_f32_e32 v153, v153
	v_mul_f32_e32 v151, 0x437f0000, v151
	v_mul_f32_e32 v152, 0x437f0000, v152
	v_cvt_pk_u8_f32 v151, v151, 0, 0
	v_mul_f32_e32 v153, 0x437f0000, v153
	v_cvt_pk_u8_f32 v151, v152, 1, v151
	v_mul_f32_e32 v152, 0xbfb8aa3b, v82
	v_exp_f32_e32 v152, v152
	s_nop 0
	v_add_f32_e32 v152, 1.0, v152
	v_rcp_f32_e32 v152, v152
	s_nop 0
	v_mul_f32_e32 v152, 0x437f0000, v152
	s_nop 0
	v_cvt_pk_u8_f32 v151, v152, 2, v151
	v_cvt_pk_u8_f32 v151, v153, 3, v151
	ds_write_b32 v150, v151 offset:8192
	v_mul_f32_e32 v151, 0xbfb8aa3b, v76
	v_mul_f32_e32 v152, 0xbfb8aa3b, v77
	v_exp_f32_e32 v151, v151
	v_exp_f32_e32 v152, v152
	v_mul_f32_e32 v153, 0xbfb8aa3b, v79
	v_exp_f32_e32 v153, v153
	v_add_f32_e32 v151, 1.0, v151
	v_add_f32_e32 v152, 1.0, v152
	v_rcp_f32_e32 v151, v151
	v_rcp_f32_e32 v152, v152
	v_add_f32_e32 v153, 1.0, v153
	v_rcp_f32_e32 v153, v153
	v_mul_f32_e32 v151, 0x437f0000, v151
	v_mul_f32_e32 v152, 0x437f0000, v152
	v_cvt_pk_u8_f32 v151, v151, 0, 0
	v_mul_f32_e32 v153, 0x437f0000, v153
	v_cvt_pk_u8_f32 v151, v152, 1, v151
	v_mul_f32_e32 v152, 0xbfb8aa3b, v78
	v_exp_f32_e32 v152, v152
	s_nop 0
	v_add_f32_e32 v152, 1.0, v152
	v_rcp_f32_e32 v152, v152
	s_nop 0
	v_mul_f32_e32 v152, 0x437f0000, v152
	s_nop 0
	v_cvt_pk_u8_f32 v151, v152, 2, v151
	v_cvt_pk_u8_f32 v151, v153, 3, v151
	ds_write_b32 v147, v151 offset:12288
	v_mul_f32_e32 v151, 0xbfb8aa3b, v72
	v_mul_f32_e32 v152, 0xbfb8aa3b, v73
	v_exp_f32_e32 v151, v151
	v_exp_f32_e32 v152, v152
	v_mul_f32_e32 v153, 0xbfb8aa3b, v75
	v_exp_f32_e32 v153, v153
	v_add_f32_e32 v151, 1.0, v151
	v_add_f32_e32 v152, 1.0, v152
	v_rcp_f32_e32 v151, v151
	v_rcp_f32_e32 v152, v152
	v_add_f32_e32 v153, 1.0, v153
	v_rcp_f32_e32 v153, v153
	v_mul_f32_e32 v151, 0x437f0000, v151
	v_mul_f32_e32 v152, 0x437f0000, v152
	v_cvt_pk_u8_f32 v151, v151, 0, 0
	v_mul_f32_e32 v153, 0x437f0000, v153
	v_cvt_pk_u8_f32 v151, v152, 1, v151
	v_mul_f32_e32 v152, 0xbfb8aa3b, v74
	v_exp_f32_e32 v152, v152
	s_nop 0
	v_add_f32_e32 v152, 1.0, v152
	v_rcp_f32_e32 v152, v152
	s_nop 0
	v_mul_f32_e32 v152, 0x437f0000, v152
	s_nop 0
	v_cvt_pk_u8_f32 v151, v152, 2, v151
	v_cvt_pk_u8_f32 v151, v153, 3, v151
	ds_write_b32 v148, v151 offset:12288
	v_mul_f32_e32 v151, 0xbfb8aa3b, v68
	v_mul_f32_e32 v152, 0xbfb8aa3b, v69
	v_exp_f32_e32 v151, v151
	v_exp_f32_e32 v152, v152
	v_mul_f32_e32 v153, 0xbfb8aa3b, v71
	v_exp_f32_e32 v153, v153
	v_add_f32_e32 v151, 1.0, v151
	v_add_f32_e32 v152, 1.0, v152
	v_rcp_f32_e32 v151, v151
	v_rcp_f32_e32 v152, v152
	v_add_f32_e32 v153, 1.0, v153
	v_rcp_f32_e32 v153, v153
	v_mul_f32_e32 v151, 0x437f0000, v151
	v_mul_f32_e32 v152, 0x437f0000, v152
	v_cvt_pk_u8_f32 v151, v151, 0, 0
	v_mul_f32_e32 v153, 0x437f0000, v153
	v_cvt_pk_u8_f32 v151, v152, 1, v151
	v_mul_f32_e32 v152, 0xbfb8aa3b, v70
	v_exp_f32_e32 v152, v152
	s_nop 0
	v_add_f32_e32 v152, 1.0, v152
	v_rcp_f32_e32 v152, v152
	s_nop 0
	v_mul_f32_e32 v152, 0x437f0000, v152
	s_nop 0
	v_cvt_pk_u8_f32 v151, v152, 2, v151
	v_cvt_pk_u8_f32 v151, v153, 3, v151
	ds_write_b32 v149, v151 offset:12288
	v_mul_f32_e32 v151, 0xbfb8aa3b, v64
	v_mul_f32_e32 v152, 0xbfb8aa3b, v65
	v_exp_f32_e32 v151, v151
	v_exp_f32_e32 v152, v152
	v_mul_f32_e32 v153, 0xbfb8aa3b, v67
	v_exp_f32_e32 v153, v153
	v_add_f32_e32 v151, 1.0, v151
	v_add_f32_e32 v152, 1.0, v152
	v_rcp_f32_e32 v151, v151
	v_rcp_f32_e32 v152, v152
	v_add_f32_e32 v153, 1.0, v153
	v_rcp_f32_e32 v153, v153
	v_mul_f32_e32 v151, 0x437f0000, v151
	v_mul_f32_e32 v152, 0x437f0000, v152
	v_cvt_pk_u8_f32 v151, v151, 0, 0
	v_mul_f32_e32 v153, 0x437f0000, v153
	v_cvt_pk_u8_f32 v151, v152, 1, v151
	v_mul_f32_e32 v152, 0xbfb8aa3b, v66
	v_exp_f32_e32 v152, v152
	s_nop 0
	v_add_f32_e32 v152, 1.0, v152
	v_rcp_f32_e32 v152, v152
	s_nop 0
	v_mul_f32_e32 v152, 0x437f0000, v152
	s_nop 0
	v_cvt_pk_u8_f32 v151, v152, 2, v151
	v_cvt_pk_u8_f32 v151, v153, 3, v151
	ds_write_b32 v150, v151 offset:12288
	v_mul_f32_e32 v151, 0xbfb8aa3b, v60
	v_mul_f32_e32 v152, 0xbfb8aa3b, v61
	v_exp_f32_e32 v151, v151
	v_exp_f32_e32 v152, v152
	v_mul_f32_e32 v153, 0xbfb8aa3b, v63
	v_exp_f32_e32 v153, v153
	v_add_f32_e32 v151, 1.0, v151
	v_add_f32_e32 v152, 1.0, v152
	v_rcp_f32_e32 v151, v151
	v_rcp_f32_e32 v152, v152
	v_add_f32_e32 v153, 1.0, v153
	v_rcp_f32_e32 v153, v153
	v_mul_f32_e32 v151, 0x437f0000, v151
	v_mul_f32_e32 v152, 0x437f0000, v152
	v_cvt_pk_u8_f32 v151, v151, 0, 0
	v_mul_f32_e32 v153, 0x437f0000, v153
	v_cvt_pk_u8_f32 v151, v152, 1, v151
	v_mul_f32_e32 v152, 0xbfb8aa3b, v62
	v_exp_f32_e32 v152, v152
	s_nop 0
	v_add_f32_e32 v152, 1.0, v152
	v_rcp_f32_e32 v152, v152
	s_nop 0
	v_mul_f32_e32 v152, 0x437f0000, v152
	s_nop 0
	v_cvt_pk_u8_f32 v151, v152, 2, v151
	v_cvt_pk_u8_f32 v151, v153, 3, v151
	ds_write_b32 v147, v151 offset:16384
	v_mul_f32_e32 v151, 0xbfb8aa3b, v56
	v_mul_f32_e32 v152, 0xbfb8aa3b, v57
	v_exp_f32_e32 v151, v151
	v_exp_f32_e32 v152, v152
	v_mul_f32_e32 v153, 0xbfb8aa3b, v59
	v_exp_f32_e32 v153, v153
	v_add_f32_e32 v151, 1.0, v151
	v_add_f32_e32 v152, 1.0, v152
	v_rcp_f32_e32 v151, v151
	v_rcp_f32_e32 v152, v152
	v_add_f32_e32 v153, 1.0, v153
	v_rcp_f32_e32 v153, v153
	v_mul_f32_e32 v151, 0x437f0000, v151
	v_mul_f32_e32 v152, 0x437f0000, v152
	v_cvt_pk_u8_f32 v151, v151, 0, 0
	v_mul_f32_e32 v153, 0x437f0000, v153
	v_cvt_pk_u8_f32 v151, v152, 1, v151
	v_mul_f32_e32 v152, 0xbfb8aa3b, v58
	v_exp_f32_e32 v152, v152
	s_nop 0
	v_add_f32_e32 v152, 1.0, v152
	v_rcp_f32_e32 v152, v152
	s_nop 0
	v_mul_f32_e32 v152, 0x437f0000, v152
	s_nop 0
	v_cvt_pk_u8_f32 v151, v152, 2, v151
	v_cvt_pk_u8_f32 v151, v153, 3, v151
	ds_write_b32 v148, v151 offset:16384
	v_mul_f32_e32 v151, 0xbfb8aa3b, v52
	v_mul_f32_e32 v152, 0xbfb8aa3b, v53
	v_exp_f32_e32 v151, v151
	v_exp_f32_e32 v152, v152
	v_mul_f32_e32 v153, 0xbfb8aa3b, v55
	v_exp_f32_e32 v153, v153
	v_add_f32_e32 v151, 1.0, v151
	v_add_f32_e32 v152, 1.0, v152
	v_rcp_f32_e32 v151, v151
	v_rcp_f32_e32 v152, v152
	v_add_f32_e32 v153, 1.0, v153
	v_rcp_f32_e32 v153, v153
	v_mul_f32_e32 v151, 0x437f0000, v151
	v_mul_f32_e32 v152, 0x437f0000, v152
	v_cvt_pk_u8_f32 v151, v151, 0, 0
	v_mul_f32_e32 v153, 0x437f0000, v153
	v_cvt_pk_u8_f32 v151, v152, 1, v151
	v_mul_f32_e32 v152, 0xbfb8aa3b, v54
	v_exp_f32_e32 v152, v152
	s_nop 0
	v_add_f32_e32 v152, 1.0, v152
	v_rcp_f32_e32 v152, v152
	s_nop 0
	v_mul_f32_e32 v152, 0x437f0000, v152
	s_nop 0
	v_cvt_pk_u8_f32 v151, v152, 2, v151
	v_cvt_pk_u8_f32 v151, v153, 3, v151
	ds_write_b32 v149, v151 offset:16384
	v_mul_f32_e32 v151, 0xbfb8aa3b, v48
	v_mul_f32_e32 v152, 0xbfb8aa3b, v49
	v_exp_f32_e32 v151, v151
	v_exp_f32_e32 v152, v152
	v_mul_f32_e32 v153, 0xbfb8aa3b, v51
	v_exp_f32_e32 v153, v153
	v_add_f32_e32 v151, 1.0, v151
	v_add_f32_e32 v152, 1.0, v152
	v_rcp_f32_e32 v151, v151
	v_rcp_f32_e32 v152, v152
	v_add_f32_e32 v153, 1.0, v153
	v_rcp_f32_e32 v153, v153
	v_mul_f32_e32 v151, 0x437f0000, v151
	v_mul_f32_e32 v152, 0x437f0000, v152
	v_cvt_pk_u8_f32 v151, v151, 0, 0
	v_mul_f32_e32 v153, 0x437f0000, v153
	v_cvt_pk_u8_f32 v151, v152, 1, v151
	v_mul_f32_e32 v152, 0xbfb8aa3b, v50
	v_exp_f32_e32 v152, v152
	s_nop 0
	v_add_f32_e32 v152, 1.0, v152
	v_rcp_f32_e32 v152, v152
	s_nop 0
	v_mul_f32_e32 v152, 0x437f0000, v152
	s_nop 0
	v_cvt_pk_u8_f32 v151, v152, 2, v151
	v_cvt_pk_u8_f32 v151, v153, 3, v151
	ds_write_b32 v150, v151 offset:16384
	v_mul_f32_e32 v151, 0xbfb8aa3b, v44
	v_mul_f32_e32 v152, 0xbfb8aa3b, v45
	v_exp_f32_e32 v151, v151
	v_exp_f32_e32 v152, v152
	v_mul_f32_e32 v153, 0xbfb8aa3b, v47
	v_exp_f32_e32 v153, v153
	v_add_f32_e32 v151, 1.0, v151
	v_add_f32_e32 v152, 1.0, v152
	v_rcp_f32_e32 v151, v151
	v_rcp_f32_e32 v152, v152
	v_add_f32_e32 v153, 1.0, v153
	v_rcp_f32_e32 v153, v153
	v_mul_f32_e32 v151, 0x437f0000, v151
	v_mul_f32_e32 v152, 0x437f0000, v152
	v_cvt_pk_u8_f32 v151, v151, 0, 0
	v_mul_f32_e32 v153, 0x437f0000, v153
	v_cvt_pk_u8_f32 v151, v152, 1, v151
	v_mul_f32_e32 v152, 0xbfb8aa3b, v46
	v_exp_f32_e32 v152, v152
	s_nop 0
	v_add_f32_e32 v152, 1.0, v152
	v_rcp_f32_e32 v152, v152
	s_nop 0
	v_mul_f32_e32 v152, 0x437f0000, v152
	s_nop 0
	v_cvt_pk_u8_f32 v151, v152, 2, v151
	v_cvt_pk_u8_f32 v151, v153, 3, v151
	ds_write_b32 v147, v151 offset:20480
	v_mul_f32_e32 v151, 0xbfb8aa3b, v40
	v_mul_f32_e32 v152, 0xbfb8aa3b, v41
	v_exp_f32_e32 v151, v151
	v_exp_f32_e32 v152, v152
	v_mul_f32_e32 v153, 0xbfb8aa3b, v43
	v_exp_f32_e32 v153, v153
	v_add_f32_e32 v151, 1.0, v151
	v_add_f32_e32 v152, 1.0, v152
	v_rcp_f32_e32 v151, v151
	v_rcp_f32_e32 v152, v152
	v_add_f32_e32 v153, 1.0, v153
	v_rcp_f32_e32 v153, v153
	v_mul_f32_e32 v151, 0x437f0000, v151
	v_mul_f32_e32 v152, 0x437f0000, v152
	v_cvt_pk_u8_f32 v151, v151, 0, 0
	v_mul_f32_e32 v153, 0x437f0000, v153
	v_cvt_pk_u8_f32 v151, v152, 1, v151
	v_mul_f32_e32 v152, 0xbfb8aa3b, v42
	v_exp_f32_e32 v152, v152
	s_nop 0
	v_add_f32_e32 v152, 1.0, v152
	v_rcp_f32_e32 v152, v152
	s_nop 0
	v_mul_f32_e32 v152, 0x437f0000, v152
	s_nop 0
	v_cvt_pk_u8_f32 v151, v152, 2, v151
	v_cvt_pk_u8_f32 v151, v153, 3, v151
	ds_write_b32 v148, v151 offset:20480
	v_mul_f32_e32 v151, 0xbfb8aa3b, v36
	v_mul_f32_e32 v152, 0xbfb8aa3b, v37
	v_exp_f32_e32 v151, v151
	v_exp_f32_e32 v152, v152
	v_mul_f32_e32 v153, 0xbfb8aa3b, v39
	v_exp_f32_e32 v153, v153
	v_add_f32_e32 v151, 1.0, v151
	v_add_f32_e32 v152, 1.0, v152
	v_rcp_f32_e32 v151, v151
	v_rcp_f32_e32 v152, v152
	v_add_f32_e32 v153, 1.0, v153
	v_rcp_f32_e32 v153, v153
	v_mul_f32_e32 v151, 0x437f0000, v151
	v_mul_f32_e32 v152, 0x437f0000, v152
	v_cvt_pk_u8_f32 v151, v151, 0, 0
	v_mul_f32_e32 v153, 0x437f0000, v153
	v_cvt_pk_u8_f32 v151, v152, 1, v151
	v_mul_f32_e32 v152, 0xbfb8aa3b, v38
	v_exp_f32_e32 v152, v152
	s_nop 0
	v_add_f32_e32 v152, 1.0, v152
	v_rcp_f32_e32 v152, v152
	s_nop 0
	v_mul_f32_e32 v152, 0x437f0000, v152
	s_nop 0
	v_cvt_pk_u8_f32 v151, v152, 2, v151
	v_cvt_pk_u8_f32 v151, v153, 3, v151
	ds_write_b32 v149, v151 offset:20480
	v_mul_f32_e32 v151, 0xbfb8aa3b, v32
	v_mul_f32_e32 v152, 0xbfb8aa3b, v33
	v_exp_f32_e32 v151, v151
	v_exp_f32_e32 v152, v152
	v_mul_f32_e32 v153, 0xbfb8aa3b, v35
	v_exp_f32_e32 v153, v153
	v_add_f32_e32 v151, 1.0, v151
	v_add_f32_e32 v152, 1.0, v152
	v_rcp_f32_e32 v151, v151
	v_rcp_f32_e32 v152, v152
	v_add_f32_e32 v153, 1.0, v153
	v_rcp_f32_e32 v153, v153
	v_mul_f32_e32 v151, 0x437f0000, v151
	v_mul_f32_e32 v152, 0x437f0000, v152
	v_cvt_pk_u8_f32 v151, v151, 0, 0
	v_mul_f32_e32 v153, 0x437f0000, v153
	v_cvt_pk_u8_f32 v151, v152, 1, v151
	v_mul_f32_e32 v152, 0xbfb8aa3b, v34
	v_exp_f32_e32 v152, v152
	s_nop 0
	v_add_f32_e32 v152, 1.0, v152
	v_rcp_f32_e32 v152, v152
	s_nop 0
	v_mul_f32_e32 v152, 0x437f0000, v152
	s_nop 0
	v_cvt_pk_u8_f32 v151, v152, 2, v151
	v_cvt_pk_u8_f32 v151, v153, 3, v151
	ds_write_b32 v150, v151 offset:20480
	v_mul_f32_e32 v151, 0xbfb8aa3b, v28
	v_mul_f32_e32 v152, 0xbfb8aa3b, v29
	v_exp_f32_e32 v151, v151
	v_exp_f32_e32 v152, v152
	v_mul_f32_e32 v153, 0xbfb8aa3b, v31
	v_exp_f32_e32 v153, v153
	v_add_f32_e32 v151, 1.0, v151
	v_add_f32_e32 v152, 1.0, v152
	v_rcp_f32_e32 v151, v151
	v_rcp_f32_e32 v152, v152
	v_add_f32_e32 v153, 1.0, v153
	v_rcp_f32_e32 v153, v153
	v_mul_f32_e32 v151, 0x437f0000, v151
	v_mul_f32_e32 v152, 0x437f0000, v152
	v_cvt_pk_u8_f32 v151, v151, 0, 0
	v_mul_f32_e32 v153, 0x437f0000, v153
	v_cvt_pk_u8_f32 v151, v152, 1, v151
	v_mul_f32_e32 v152, 0xbfb8aa3b, v30
	v_exp_f32_e32 v152, v152
	s_nop 0
	v_add_f32_e32 v152, 1.0, v152
	v_rcp_f32_e32 v152, v152
	s_nop 0
	v_mul_f32_e32 v152, 0x437f0000, v152
	s_nop 0
	v_cvt_pk_u8_f32 v151, v152, 2, v151
	v_cvt_pk_u8_f32 v151, v153, 3, v151
	ds_write_b32 v147, v151 offset:24576
	v_mul_f32_e32 v151, 0xbfb8aa3b, v24
	v_mul_f32_e32 v152, 0xbfb8aa3b, v25
	v_exp_f32_e32 v151, v151
	v_exp_f32_e32 v152, v152
	v_mul_f32_e32 v153, 0xbfb8aa3b, v27
	v_exp_f32_e32 v153, v153
	v_add_f32_e32 v151, 1.0, v151
	v_add_f32_e32 v152, 1.0, v152
	v_rcp_f32_e32 v151, v151
	v_rcp_f32_e32 v152, v152
	v_add_f32_e32 v153, 1.0, v153
	v_rcp_f32_e32 v153, v153
	v_mul_f32_e32 v151, 0x437f0000, v151
	v_mul_f32_e32 v152, 0x437f0000, v152
	v_cvt_pk_u8_f32 v151, v151, 0, 0
	v_mul_f32_e32 v153, 0x437f0000, v153
	v_cvt_pk_u8_f32 v151, v152, 1, v151
	v_mul_f32_e32 v152, 0xbfb8aa3b, v26
	v_exp_f32_e32 v152, v152
	s_nop 0
	v_add_f32_e32 v152, 1.0, v152
	v_rcp_f32_e32 v152, v152
	s_nop 0
	v_mul_f32_e32 v152, 0x437f0000, v152
	s_nop 0
	v_cvt_pk_u8_f32 v151, v152, 2, v151
	v_cvt_pk_u8_f32 v151, v153, 3, v151
	ds_write_b32 v148, v151 offset:24576
	v_mul_f32_e32 v151, 0xbfb8aa3b, v20
	v_mul_f32_e32 v152, 0xbfb8aa3b, v21
	v_exp_f32_e32 v151, v151
	v_exp_f32_e32 v152, v152
	v_mul_f32_e32 v153, 0xbfb8aa3b, v23
	v_exp_f32_e32 v153, v153
	v_add_f32_e32 v151, 1.0, v151
	v_add_f32_e32 v152, 1.0, v152
	v_rcp_f32_e32 v151, v151
	v_rcp_f32_e32 v152, v152
	v_add_f32_e32 v153, 1.0, v153
	v_rcp_f32_e32 v153, v153
	v_mul_f32_e32 v151, 0x437f0000, v151
	v_mul_f32_e32 v152, 0x437f0000, v152
	v_cvt_pk_u8_f32 v151, v151, 0, 0
	v_mul_f32_e32 v153, 0x437f0000, v153
	v_cvt_pk_u8_f32 v151, v152, 1, v151
	v_mul_f32_e32 v152, 0xbfb8aa3b, v22
	v_exp_f32_e32 v152, v152
	s_nop 0
	v_add_f32_e32 v152, 1.0, v152
	v_rcp_f32_e32 v152, v152
	s_nop 0
	v_mul_f32_e32 v152, 0x437f0000, v152
	s_nop 0
	v_cvt_pk_u8_f32 v151, v152, 2, v151
	v_cvt_pk_u8_f32 v151, v153, 3, v151
	ds_write_b32 v149, v151 offset:24576
	v_mul_f32_e32 v151, 0xbfb8aa3b, v16
	v_mul_f32_e32 v152, 0xbfb8aa3b, v17
	v_exp_f32_e32 v151, v151
	v_exp_f32_e32 v152, v152
	v_mul_f32_e32 v153, 0xbfb8aa3b, v19
	v_exp_f32_e32 v153, v153
	v_add_f32_e32 v151, 1.0, v151
	v_add_f32_e32 v152, 1.0, v152
	v_rcp_f32_e32 v151, v151
	v_rcp_f32_e32 v152, v152
	v_add_f32_e32 v153, 1.0, v153
	v_rcp_f32_e32 v153, v153
	v_mul_f32_e32 v151, 0x437f0000, v151
	v_mul_f32_e32 v152, 0x437f0000, v152
	v_cvt_pk_u8_f32 v151, v151, 0, 0
	v_mul_f32_e32 v153, 0x437f0000, v153
	v_cvt_pk_u8_f32 v151, v152, 1, v151
	v_mul_f32_e32 v152, 0xbfb8aa3b, v18
	v_exp_f32_e32 v152, v152
	s_nop 0
	v_add_f32_e32 v152, 1.0, v152
	v_rcp_f32_e32 v152, v152
	s_nop 0
	v_mul_f32_e32 v152, 0x437f0000, v152
	s_nop 0
	v_cvt_pk_u8_f32 v151, v152, 2, v151
	v_cvt_pk_u8_f32 v151, v153, 3, v151
	ds_write_b32 v150, v151 offset:24576
	v_mul_f32_e32 v151, 0xbfb8aa3b, v12
	v_mul_f32_e32 v152, 0xbfb8aa3b, v13
	v_exp_f32_e32 v151, v151
	v_exp_f32_e32 v152, v152
	v_mul_f32_e32 v153, 0xbfb8aa3b, v15
	v_exp_f32_e32 v153, v153
	v_add_f32_e32 v151, 1.0, v151
	v_add_f32_e32 v152, 1.0, v152
	v_rcp_f32_e32 v151, v151
	v_rcp_f32_e32 v152, v152
	v_add_f32_e32 v153, 1.0, v153
	v_rcp_f32_e32 v153, v153
	v_mul_f32_e32 v151, 0x437f0000, v151
	v_mul_f32_e32 v152, 0x437f0000, v152
	v_cvt_pk_u8_f32 v151, v151, 0, 0
	v_mul_f32_e32 v153, 0x437f0000, v153
	v_cvt_pk_u8_f32 v151, v152, 1, v151
	v_mul_f32_e32 v152, 0xbfb8aa3b, v14
	v_exp_f32_e32 v152, v152
	s_nop 0
	v_add_f32_e32 v152, 1.0, v152
	v_rcp_f32_e32 v152, v152
	s_nop 0
	v_mul_f32_e32 v152, 0x437f0000, v152
	s_nop 0
	v_cvt_pk_u8_f32 v151, v152, 2, v151
	v_cvt_pk_u8_f32 v151, v153, 3, v151
	ds_write_b32 v147, v151 offset:28672
	v_mul_f32_e32 v147, 0xbfb8aa3b, v8
	v_mul_f32_e32 v151, 0xbfb8aa3b, v9
	v_exp_f32_e32 v147, v147
	v_exp_f32_e32 v151, v151
	v_mul_f32_e32 v152, 0xbfb8aa3b, v11
	v_exp_f32_e32 v152, v152
	v_add_f32_e32 v147, 1.0, v147
	v_add_f32_e32 v151, 1.0, v151
	v_rcp_f32_e32 v147, v147
	v_rcp_f32_e32 v151, v151
	v_add_f32_e32 v152, 1.0, v152
	v_rcp_f32_e32 v152, v152
	v_mul_f32_e32 v147, 0x437f0000, v147
	v_mul_f32_e32 v151, 0x437f0000, v151
	v_cvt_pk_u8_f32 v147, v147, 0, 0
	v_mul_f32_e32 v152, 0x437f0000, v152
	v_cvt_pk_u8_f32 v147, v151, 1, v147
	v_mul_f32_e32 v151, 0xbfb8aa3b, v10
	v_exp_f32_e32 v151, v151
	s_nop 0
	v_add_f32_e32 v151, 1.0, v151
	v_rcp_f32_e32 v151, v151
	s_nop 0
	v_mul_f32_e32 v151, 0x437f0000, v151
	s_nop 0
	v_cvt_pk_u8_f32 v147, v151, 2, v147
	v_cvt_pk_u8_f32 v147, v152, 3, v147
	ds_write_b32 v148, v147 offset:28672
	v_mul_f32_e32 v147, 0xbfb8aa3b, v4
	v_mul_f32_e32 v148, 0xbfb8aa3b, v5
	v_exp_f32_e32 v147, v147
	v_exp_f32_e32 v148, v148
	v_mul_f32_e32 v151, 0xbfb8aa3b, v7
	v_exp_f32_e32 v151, v151
	v_add_f32_e32 v147, 1.0, v147
	v_add_f32_e32 v148, 1.0, v148
	v_rcp_f32_e32 v147, v147
	v_rcp_f32_e32 v148, v148
	v_add_f32_e32 v151, 1.0, v151
	v_rcp_f32_e32 v151, v151
	v_mul_f32_e32 v147, 0x437f0000, v147
	v_mul_f32_e32 v148, 0x437f0000, v148
	v_cvt_pk_u8_f32 v147, v147, 0, 0
	v_mul_f32_e32 v151, 0x437f0000, v151
	v_cvt_pk_u8_f32 v147, v148, 1, v147
	v_mul_f32_e32 v148, 0xbfb8aa3b, v6
	v_exp_f32_e32 v148, v148
	s_nop 0
	v_add_f32_e32 v148, 1.0, v148
	v_rcp_f32_e32 v148, v148
	s_nop 0
	v_mul_f32_e32 v148, 0x437f0000, v148
	s_nop 0
	v_cvt_pk_u8_f32 v147, v148, 2, v147
	v_cvt_pk_u8_f32 v147, v151, 3, v147
	ds_write_b32 v149, v147 offset:28672
	v_mul_f32_e32 v147, 0xbfb8aa3b, v0
	v_mul_f32_e32 v148, 0xbfb8aa3b, v1
	v_exp_f32_e32 v147, v147
	v_exp_f32_e32 v148, v148
	v_mul_f32_e32 v149, 0xbfb8aa3b, v3
	v_exp_f32_e32 v149, v149
	v_add_f32_e32 v147, 1.0, v147
	v_add_f32_e32 v148, 1.0, v148
	v_rcp_f32_e32 v147, v147
	v_rcp_f32_e32 v148, v148
	v_add_f32_e32 v149, 1.0, v149
	v_rcp_f32_e32 v149, v149
	v_mul_f32_e32 v147, 0x437f0000, v147
	v_mul_f32_e32 v148, 0x437f0000, v148
	v_cvt_pk_u8_f32 v147, v147, 0, 0
	v_mul_f32_e32 v149, 0x437f0000, v149
	v_cvt_pk_u8_f32 v147, v148, 1, v147
	v_mul_f32_e32 v148, 0xbfb8aa3b, v2
	v_exp_f32_e32 v148, v148
	v_ashrrev_i32_e32 v151, 4, v145
	v_add_f32_e32 v148, 1.0, v148
	v_rcp_f32_e32 v148, v148
	s_nop 0
	v_mul_f32_e32 v148, 0x437f0000, v148
	s_nop 0
	v_cvt_pk_u8_f32 v147, v148, 2, v147
	v_cvt_pk_u8_f32 v147, v149, 3, v147
	ds_write_b32 v150, v147 offset:28672
	v_and_b32_e32 v150, 0xf0, v146
	v_xor_b32_e32 v146, v151, v144
	v_lshlrev_b32_e32 v146, 4, v146
	v_and_b32_e32 v146, 0xf0, v146
	v_lshl_or_b32 v146, v151, 8, v146
	v_add_u32_e32 v146, 0x10000, v146
	s_waitcnt lgkmcnt(0)
	s_barrier
	s_waitcnt vmcnt(0)
	ds_read_b128 v[146:149], v146
	v_mad_u64_u32 v[152:153], s[34:35], v151, s33, v[150:151]
	s_waitcnt lgkmcnt(0)
	buffer_store_dwordx4 v[146:149], v152, s[16:19], 0 offen sc1
	s_nop 1
	v_add_u32_e32 v146, 0x200, v145
	v_ashrrev_i32_e32 v151, 4, v146
	v_xor_b32_e32 v146, v151, v144
	v_lshlrev_b32_e32 v146, 4, v146
	v_and_b32_e32 v146, 0xf0, v146
	v_lshl_or_b32 v146, v151, 8, v146
	v_add_u32_e32 v146, 0x10000, v146
	ds_read_b128 v[146:149], v146
	v_mad_u64_u32 v[152:153], s[34:35], v151, s33, v[150:151]
	s_waitcnt lgkmcnt(0)
	buffer_store_dwordx4 v[146:149], v152, s[16:19], 0 offen sc1
	s_nop 1
	v_add_u32_e32 v146, 0x400, v145
	v_ashrrev_i32_e32 v151, 4, v146
	v_xor_b32_e32 v146, v151, v144
	v_lshlrev_b32_e32 v146, 4, v146
	v_and_b32_e32 v146, 0xf0, v146
	v_lshl_or_b32 v146, v151, 8, v146
	v_add_u32_e32 v146, 0x10000, v146
	ds_read_b128 v[146:149], v146
	v_mad_u64_u32 v[152:153], s[34:35], v151, s33, v[150:151]
	s_waitcnt lgkmcnt(0)
	buffer_store_dwordx4 v[146:149], v152, s[16:19], 0 offen sc1
	s_nop 1
	v_add_u32_e32 v146, 0x600, v145
	v_ashrrev_i32_e32 v151, 4, v146
	v_xor_b32_e32 v146, v151, v144
	v_lshlrev_b32_e32 v146, 4, v146
	v_and_b32_e32 v146, 0xf0, v146
	v_lshl_or_b32 v146, v151, 8, v146
	v_add_u32_e32 v146, 0x10000, v146
	ds_read_b128 v[146:149], v146
	v_mad_u64_u32 v[152:153], s[34:35], v151, s33, v[150:151]
	s_waitcnt lgkmcnt(0)
	buffer_store_dwordx4 v[146:149], v152, s[16:19], 0 offen sc1
	s_nop 1
	v_add_u32_e32 v146, 0x800, v145
	v_ashrrev_i32_e32 v151, 4, v146
	v_xor_b32_e32 v146, v151, v144
	v_lshlrev_b32_e32 v146, 4, v146
	v_and_b32_e32 v146, 0xf0, v146
	v_lshl_or_b32 v146, v151, 8, v146
	v_add_u32_e32 v146, 0x10000, v146
	ds_read_b128 v[146:149], v146
	v_mad_u64_u32 v[152:153], s[34:35], v151, s33, v[150:151]
	s_waitcnt lgkmcnt(0)
	buffer_store_dwordx4 v[146:149], v152, s[16:19], 0 offen sc1
	s_nop 1
	v_add_u32_e32 v146, 0xa00, v145
	v_ashrrev_i32_e32 v151, 4, v146
	v_xor_b32_e32 v146, v151, v144
	v_lshlrev_b32_e32 v146, 4, v146
	v_and_b32_e32 v146, 0xf0, v146
	v_lshl_or_b32 v146, v151, 8, v146
	v_add_u32_e32 v146, 0x10000, v146
	ds_read_b128 v[146:149], v146
	v_mad_u64_u32 v[152:153], s[34:35], v151, s33, v[150:151]
	s_waitcnt lgkmcnt(0)
	buffer_store_dwordx4 v[146:149], v152, s[16:19], 0 offen sc1
	s_nop 1
	v_add_u32_e32 v146, 0xc00, v145
	v_ashrrev_i32_e32 v151, 4, v146
	v_xor_b32_e32 v146, v151, v144
	v_lshlrev_b32_e32 v146, 4, v146
	v_and_b32_e32 v146, 0xf0, v146
	v_lshl_or_b32 v146, v151, 8, v146
	v_add_u32_e32 v146, 0x10000, v146
	ds_read_b128 v[146:149], v146
	v_mad_u64_u32 v[152:153], s[34:35], v151, s33, v[150:151]
	v_add_u32_e32 v145, 0xe00, v145
	s_waitcnt lgkmcnt(0)
	buffer_store_dwordx4 v[146:149], v152, s[16:19], 0 offen sc1
	s_nop 1
	v_ashrrev_i32_e32 v148, 4, v145
	v_xor_b32_e32 v144, v148, v144
	v_lshlrev_b32_e32 v144, 4, v144
	v_and_b32_e32 v144, 0xf0, v144
	v_lshl_or_b32 v144, v148, 8, v144
	v_add_u32_e32 v144, 0x10000, v144
	ds_read_b128 v[144:147], v144
	v_mad_u64_u32 v[148:149], s[34:35], v148, s33, v[150:151]
	s_mov_b64 s[34:35], 0
	s_waitcnt lgkmcnt(0)
	buffer_store_dwordx4 v[144:147], v148, s[16:19], 0 offen sc1
	s_waitcnt lgkmcnt(0)
	s_barrier
